# P5 a2+raw+prm plus attention queue: next unit ticket fetched early in the epilogue (atomic latency hidden), no vmcnt(0) drain at unit start
# speedup vs baseline: 1.1195x; 1.0008x over previous
; __device__ __forceinline__ int lane_id_asm() { int l; asm volatile("v_mbcnt_lo_u32_b32 %0, -1, 0\n\tv_mbcnt_hi_u32_b32 %0, -1, %0" : "=v"(l)); return l; }
; __device__ __forceinline__ int crow(int r,int hi){return (r&3)+8*(r>>2)+4*hi;}
; template<int THRL> __device__ __forceinline__ void attn_unit(int b,int h,int qb,const bf16*Q,const bf16*__restrict__ K,const bf16*__restrict__ V,bf16*O,char*shm,const int wid){
;     ...
;   {auto rr=__builtin_amdgcn_permlane32_swap(__float_as_uint(l_reg),__float_as_uint(l_reg),false,false);l_reg=__uint_as_float(rr[0])+__uint_as_float(rr[1]);}
;   if(hi==0)wsf[32+r32]=l_reg;asm volatile("s_waitcnt lgkmcnt(0)":::"memory");
;   float rli[16];
;   #pragma unroll
;   for(int r=0;r<16;++r)rli[r]=__builtin_amdgcn_rcpf(wsf[32+crow(r,hi)]);
;   bf16*Ow=O+(rowbase+q0+wid*QBLK)*PO+ocol;
;   { bf16*stg=(bf16*)(shm+LDS_OST)+wid*2048;
;     #pragma unroll
;     for(int r=0;r<16;++r){const int orow=crow(r,hi);
;       #pragma unroll
;       for(int d0=0;d0<2;++d0)stg[orow*64+d0*32+r32]=__float2bfloat16(o[d0][r]*rli[r]);}
;     asm volatile("s_waitcnt lgkmcnt(0)":::"memory");
;     #pragma unroll
;     for(int i=0;i<4;++i){const int row=i*8+(lane>>3),ch=lane&7; const u32x4 v=*(const u32x4*)(stg+row*64+ch*8); ATTN_STORE16(Ow+(long)row*PO+ch*8,v);} }
;   asm volatile("s_waitcnt lgkmcnt(0)\n\ts_barrier":::"memory");
; __global__ void __launch_bounds__(NWAVES * 64, 2) hybrid_fwd(const Args A) {
;     ...
;         for (;;) {
;             if (F.wave == 0 && lane_id_asm() == 0) misc[0] = atomicAdd(F.ctl + CW_QUEUE + 64 * rep, 1u);
;             __syncthreads(); const unsigned idx = misc[0]; __syncthreads();
;             if (idx >= 1024u) break;
;             const int qb = 15 - (int)(idx >> 6), bhv = (int)(idx & 63u);
;             attn_body::attn_unit<8>(bhv >> 4, bhv & 15, qb, Pd, Pd, Pd, (attn_body::bf16*)(F.ws + WS_O), (char*)lds, F.wave);
.LBB0_1533:
	s_add_u32 s33, s86, 0x9000000
	s_addc_u32 s42, s87, 0
	s_cmp_lt_u32 s79, 64
	s_cselect_b64 s[2:3], -1, 0
	s_lshl_b32 s4, s93, 4
	s_lshl_b32 s43, s93, 5
	s_lshl_b32 s0, s93, 8
	s_and_b32 s44, s4, 48
	s_and_b32 s6, s16, 0x1fffffe0
	s_lshl_b32 s45, s93, 10
	s_cmp_lg_u32 0, -1
	s_cselect_b32 s4, 0, 0
	s_add_i32 s46, s45, s4
	s_add_i32 s48, s0, 0
	s_mul_i32 s0, s93, 0xf00
	s_waitcnt vmcnt(0)
	v_cndmask_b32_e64 v0, 0, 1, s[2:3]
	s_add_i32 s50, 0, 0x25700
	s_mov_b32 s26, 0xfffd0000
	s_add_i32 s47, s46, 0x6000
	s_add_i32 s49, s48, s0
	v_cmp_ne_u32_e64 s[4:5], 1, v0
	v_mov_b32_e32 v1, 0
	v_mov_b32_e32 v206, s50
	s_movk_i32 s51, 0x3ff
	s_movk_i32 s52, 0xc00
	s_lshl_b32 s2, s16, 1
	s_mov_b64 s[10:11], 0x400
	s_lshl_b32 s12, s6, 1
	s_mov_b64 s[14:15], 0x800
	s_mov_b64 s[16:17], 0x30400
	s_mov_b64 s[18:19], 0x60400
	s_mov_b64 s[20:21], 0x90000
	s_mov_b64 s[22:23], 0x30000
	s_mov_b64 s[24:25], 0xf0000
	s_mov_b32 s27, -1
	s_mov_b32 s53, 0x41000000
	s_mov_b64 s[28:29], 0x60000
	s_mov_b64 s[30:31], 0xc0000
	v_mov_b32_e32 v207, 0xff800000
	v_mov_b32_e32 v209, 0x30000
	s_cmp_lg_u64 s[4:5], 0
	s_cbranch_scc1 .Lq_init_done
	s_mov_b64 s[100:101], exec
	s_mov_b64 exec, 1
	v_mov_b32_e32 v240, 1
	v_mov_b32_e32 v241, 0
	global_atomic_add v240, v241, v240, s[86:87] offset:256 sc0
	s_waitcnt vmcnt(0)
	v_readfirstlane_b32 s98, v240
	s_mov_b64 exec, s[100:101]
.Lq_init_done:
	s_branch .LBB0_1536
.LBB0_1534:
	s_or_b64 exec, exec, s[6:7]
	s_cmp_lg_u64 s[4:5], 0
	s_cbranch_scc1 .Lq_skip1
	s_mov_b64 s[100:101], exec
	s_mov_b64 exec, 1
	v_mov_b32_e32 v240, 1
	v_mov_b32_e32 v241, 0
	global_atomic_add v240, v241, v240, s[86:87] offset:256 sc0
	s_mov_b64 exec, s[100:101]
.Lq_skip1:
	s_waitcnt lgkmcnt(0)
	ds_read_b128 v[4:7], v2 offset:49280
	ds_read_b128 v[8:11], v2 offset:49312
	v_lshlrev_b32_e32 v50, 9, v213
	s_lshl_b64 s[6:7], s[0:1], 11
	v_readlane_b32 s8, v254, 15
	s_waitcnt lgkmcnt(1)
	v_rcp_f32_e32 v0, v4
	v_rcp_f32_e32 v3, v5
	v_rcp_f32_e32 v12, v6
	v_rcp_f32_e32 v13, v7
	s_waitcnt lgkmcnt(0)
	v_rcp_f32_e32 v14, v8
	ds_read_b128 v[4:7], v2 offset:49344
	v_rcp_f32_e32 v15, v9
	v_rcp_f32_e32 v48, v10
	v_rcp_f32_e32 v49, v11
	ds_read_b128 v[8:11], v2 offset:49376
	s_waitcnt lgkmcnt(1)
	v_rcp_f32_e32 v2, v4
	v_rcp_f32_e32 v4, v5
	v_rcp_f32_e32 v5, v6
	v_rcp_f32_e32 v6, v7
	s_waitcnt lgkmcnt(0)
	v_rcp_f32_e32 v7, v8
	v_rcp_f32_e32 v8, v9
	v_rcp_f32_e32 v9, v10
	v_rcp_f32_e32 v10, v11
	v_lshlrev_b32_e32 v11, 1, v212
	v_mul_f32_e32 v32, v32, v0
	v_mul_f32_e32 v0, v16, v0
	v_add3_u32 v11, s49, v11, v50
	v_cvt_pk_bf16_f32 v0, v0, s0
	ds_write_b16 v11, v0 offset:51264
	v_mul_f32_e32 v0, v33, v3
	v_cvt_pk_bf16_f32 v0, v0, s0
	ds_write_b16 v11, v0 offset:51328
	v_mul_f32_e32 v0, v17, v3
	v_cvt_pk_bf16_f32 v0, v0, s0
	ds_write_b16 v11, v0 offset:51392
	v_mul_f32_e32 v0, v34, v12
	v_cvt_pk_bf16_f32 v0, v0, s0
	ds_write_b16 v11, v0 offset:51456
	v_mul_f32_e32 v0, v18, v12
	v_cvt_pk_bf16_f32 v0, v0, s0
	ds_write_b16 v11, v0 offset:51520
	v_mul_f32_e32 v0, v35, v13
	v_cvt_pk_bf16_f32 v0, v0, s0
	ds_write_b16 v11, v0 offset:51584
	v_mul_f32_e32 v0, v19, v13
	v_cvt_pk_bf16_f32 v0, v0, s0
	ds_write_b16 v11, v0 offset:51648
	v_mul_f32_e32 v0, v36, v14
	v_cvt_pk_bf16_f32 v0, v0, s0
	ds_write_b16 v11, v0 offset:52224
	v_mul_f32_e32 v0, v20, v14
	v_cvt_pk_bf16_f32 v0, v0, s0
	ds_write_b16 v11, v0 offset:52288
	v_mul_f32_e32 v0, v37, v15
	v_cvt_pk_bf16_f32 v0, v0, s0
	ds_write_b16 v11, v0 offset:52352
	v_mul_f32_e32 v0, v21, v15
	v_cvt_pk_bf16_f32 v0, v0, s0
	ds_write_b16 v11, v0 offset:52416
	v_mul_f32_e32 v0, v38, v48
	v_cvt_pk_bf16_f32 v0, v0, s0
	ds_write_b16 v11, v0 offset:52480
	v_mul_f32_e32 v0, v22, v48
	v_cvt_pk_bf16_f32 v0, v0, s0
	ds_write_b16 v11, v0 offset:52544
	v_mul_f32_e32 v0, v39, v49
	v_cvt_pk_bf16_f32 v0, v0, s0
	ds_write_b16 v11, v0 offset:52608
	v_mul_f32_e32 v0, v23, v49
	v_cvt_pk_bf16_f32 v0, v0, s0
	ds_write_b16 v11, v0 offset:52672
	v_mul_f32_e32 v0, v40, v2
	v_cvt_pk_bf16_f32 v0, v0, s0
	ds_write_b16 v11, v0 offset:53248
	v_mul_f32_e32 v0, v24, v2
	v_cvt_pk_bf16_f32 v0, v0, s0
	ds_write_b16 v11, v0 offset:53312
	v_mul_f32_e32 v0, v41, v4
	v_cvt_pk_bf16_f32 v0, v0, s0
	ds_write_b16 v11, v0 offset:53376
	v_mul_f32_e32 v0, v25, v4
	v_cvt_pk_bf16_f32 v0, v0, s0
	ds_write_b16 v11, v0 offset:53440
	v_mul_f32_e32 v0, v42, v5
	v_cvt_pk_bf16_f32 v0, v0, s0
	ds_write_b16 v11, v0 offset:53504
	v_mul_f32_e32 v0, v26, v5
	v_cvt_pk_bf16_f32 v0, v0, s0
	ds_write_b16 v11, v0 offset:53568
	v_mul_f32_e32 v0, v43, v6
	v_cvt_pk_bf16_f32 v0, v0, s0
	ds_write_b16 v11, v0 offset:53632
	v_mul_f32_e32 v0, v27, v6
	v_cvt_pk_bf16_f32 v0, v0, s0
	ds_write_b16 v11, v0 offset:53696
	v_mul_f32_e32 v0, v44, v7
	v_cvt_pk_bf16_f32 v0, v0, s0
	ds_write_b16 v11, v0 offset:54272
	v_mul_f32_e32 v0, v28, v7
	v_cvt_pk_bf16_f32 v0, v0, s0
	ds_write_b16 v11, v0 offset:54336
	v_mul_f32_e32 v0, v45, v8
	v_cvt_pk_bf16_f32 v0, v0, s0
	ds_write_b16 v11, v0 offset:54400
	v_mul_f32_e32 v0, v29, v8
	v_cvt_pk_bf16_f32 v0, v0, s0
	ds_write_b16 v11, v0 offset:54464
	v_mul_f32_e32 v0, v46, v9
	v_cvt_pk_bf16_f32 v0, v0, s0
	ds_write_b16 v11, v0 offset:54528
	v_mul_f32_e32 v0, v30, v9
	v_cvt_pk_bf16_f32 v0, v0, s0
	ds_write_b16 v11, v0 offset:54592
	v_mul_f32_e32 v0, v47, v10
	v_cvt_pk_bf16_f32 v0, v0, s0
	ds_write_b16 v11, v0 offset:54656
	v_mul_f32_e32 v0, v31, v10
	v_cvt_pk_bf16_f32 v32, v32, s0
	v_cvt_pk_bf16_f32 v0, v0, s0
	v_readlane_b32 s9, v254, 16
	s_add_u32 s0, s8, s6
	ds_write_b16 v11, v0 offset:54720
	s_addc_u32 s3, s9, s7
	s_lshl_b32 s6, s54, 1
	v_lshlrev_b32_e32 v0, 1, v211
	s_add_u32 s6, s0, s6
	v_and_b32_e32 v0, 0x70, v0
	ds_write_b16 v11, v32 offset:51200
	s_addc_u32 s7, s3, 0
	v_ashrrev_i32_e32 v10, 3, v210
	v_add_u32_e32 v18, s49, v0
	s_waitcnt lgkmcnt(0)
	v_lshl_add_u64 v[12:13], s[6:7], 0, v[0:1]
	v_lshl_add_u32 v0, v10, 7, v18
	ds_read_b128 v[2:5], v0 offset:51200
	v_ashrrev_i32_e32 v11, 31, v10
	v_add_u32_e32 v16, 8, v10
	v_lshlrev_b64 v[6:7], 11, v[10:11]
	v_lshl_add_u32 v0, v16, 7, v18
	v_lshl_add_u64 v[14:15], v[12:13], 0, v[6:7]
	ds_read_b128 v[6:9], v0 offset:51200
	v_ashrrev_i32_e32 v17, 31, v16
	s_cmp_lg_u64 s[4:5], 0
	s_cbranch_scc1 .Lq_skip2
	s_waitcnt vmcnt(0)
	v_readfirstlane_b32 s98, v240
.Lq_skip2:
	s_waitcnt lgkmcnt(1)
	global_store_dwordx4 v[14:15], v[2:5], off
	s_mov_b64 s[6:7], 0
	s_nop 0
	v_lshlrev_b64 v[2:3], 11, v[16:17]
	v_lshl_add_u64 v[2:3], v[12:13], 0, v[2:3]
	s_waitcnt lgkmcnt(0)
	global_store_dwordx4 v[2:3], v[6:9], off
	s_nop 1
	v_add_u32_e32 v6, 16, v10
	v_lshl_add_u32 v0, v6, 7, v18
	ds_read_b128 v[2:5], v0 offset:51200
	v_ashrrev_i32_e32 v7, 31, v6
	v_add_u32_e32 v10, 24, v10
	v_lshlrev_b64 v[6:7], 11, v[6:7]
	v_lshl_add_u32 v0, v10, 7, v18
	v_lshl_add_u64 v[14:15], v[12:13], 0, v[6:7]
	ds_read_b128 v[6:9], v0 offset:51200
	v_ashrrev_i32_e32 v11, 31, v10
	s_waitcnt lgkmcnt(1)
	global_store_dwordx4 v[14:15], v[2:5], off
	s_nop 1
	v_lshlrev_b64 v[2:3], 11, v[10:11]
	v_lshl_add_u64 v[2:3], v[12:13], 0, v[2:3]
	s_waitcnt lgkmcnt(0)
	global_store_dwordx4 v[2:3], v[6:9], off
	s_waitcnt lgkmcnt(0)
	s_barrier

; __device__ __forceinline__ int lane_id_asm() { int l; asm volatile("v_mbcnt_lo_u32_b32 %0, -1, 0\n\tv_mbcnt_hi_u32_b32 %0, -1, %0" : "=v"(l)); return l; }
; __global__ void __launch_bounds__(NWAVES * 64, 2) hybrid_fwd(const Args A) {
;     ...
;         for (;;) {
;             if (F.wave == 0 && lane_id_asm() == 0) misc[0] = atomicAdd(F.ctl + CW_QUEUE + 64 * rep, 1u);
;             __syncthreads(); const unsigned idx = misc[0]; __syncthreads();
;             if (idx >= 1024u) break;
.LBB0_1536:
	s_and_b64 vcc, exec, s[4:5]
	s_cbranch_vccnz .LBB0_1542
	v_mbcnt_lo_u32_b32 v0, -1, 0
	v_mbcnt_hi_u32_b32 v0, -1, v0
	s_nop 0
	v_cmp_eq_u32_e32 vcc, 0, v0
	s_and_saveexec_b64 s[6:7], vcc
	s_cbranch_execz .LBB0_1541
	v_mov_b32_e32 v2, s50
	v_mov_b32_e32 v0, s98
	ds_write_b32 v2, v0
